# gate GEMM tiles from eight per-XCD (blockIdx&7) queues in 8x8-patch order for L2 reuse
# speedup vs baseline: 1.0533x; 1.0087x over previous
; __device__ __forceinline__ void phase_scan(KP p, int l, unsigned char* smem) {
;     ...
;     unsigned* cnt = (unsigned*)(p->ws + OFF_CNT) + l * 64;
;     for (;;) {
;         __syncthreads();
;         if (tid_ == 0) s_q = (int)atomicAdd(cnt, 1u);
.LBB0_165:
.LBB0_166:
	s_mov_b32 s2, 0
	v_writelane_b32 v234, s2, 8
	v_readlane_b32 s12, v230, 25
	v_readlane_b32 s13, v230, 26
	s_mov_b32 s14, s12
	s_lshl_b32 s12, s12, 6
	s_ashr_i32 s13, s12, 31
	s_lshl_b64 s[12:13], s[12:13], 2
	s_add_u32 s2, s58, s12
	s_addc_u32 s11, s59, s13
	s_add_u32 s78, s2, 0x28cf3600
	s_addc_u32 s79, s11, 0
	s_add_u32 s11, s58, 0x2140000
	s_addc_u32 s39, s59, 0
	s_add_u32 s12, s58, 0x29df3a00
	s_addc_u32 s13, s59, 0
	s_lshl_b32 s97, s14, 5
	s_add_u32 s84, s58, 0x1bfe0000
	s_addc_u32 s85, s59, 0
	s_lshl_b32 s94, s14, 7
	v_cmp_eq_u32_e64 s[40:41], 0, v64
	v_writelane_b32 v230, s12, 34
	s_add_i32 s95, s94, -8
	s_lshl_b32 s96, s14, 3
	v_writelane_b32 v230, s13, 35
	s_branch .LBB0_170

; __device__ __forceinline__ void phase_scan(KP p, int l, unsigned char* smem) {
;     ...
;     for (;;) {
;         __syncthreads();
;         if (tid_ == 0) s_q = (int)atomicAdd(cnt, 1u);
;         __syncthreads();
.LBB0_170:
	s_barrier
	s_nop 1
	v_readlane_b32 s2, v234, 8
	s_nop 1
	v_mov_b32_e32 v236, s2
	s_and_saveexec_b64 s[14:15], s[40:41]
	s_cbranch_execz .LBB0_174
	s_mov_b64 s[18:19], exec
	v_mbcnt_lo_u32_b32 v0, s18, 0
	v_mbcnt_hi_u32_b32 v0, s19, v0
	v_cmp_eq_u32_e32 vcc, 0, v0
	s_and_saveexec_b64 s[12:13], vcc
	s_cbranch_execz .LBB0_173
	s_bcnt1_i32_b64 s2, s[18:19]
	v_mov_b32_e32 v1, s2
	global_atomic_add v1, v236, v1, s[78:79] sc0

; __device__ __forceinline__ int tidx() { int t = threadIdx.x; asm volatile("" : "+v"(t)); return t; }
; __device__ __forceinline__ void gate_tile(int t, const bf16_t* xb, const bf16_t* Wg, bf16_t* G, bf16_t* sm) {
;     const int tid_ = tidx();
;     const int lane = tid_ & 63, wid = tid_ >> 6, wr = wid >> 1, wc = wid & 1, fr = lane & 15, fq = lane >> 4;
;     const int tm = t >> 5, tn = t & 31;
;     f32x4 acc[4][4]; zero_acc<4>(acc);
;     gemm_tile<4>(acc, xb + (size_t)tm * 128 * 1024, 1024, Wg + (size_t)tn * 128 * 1024, 1024, 1024, sm);
; __device__ __forceinline__ void phase_scan(KP p, int l, unsigned char* smem) {
;     ...
;         __syncthreads();
;         const int t = s_q;
;         const int NGT = 136 * 32, NAT = 1152, NMV = 256;
;         if (t >= NGT + NAT + NMV) break;
;         if (t < NMV) misc_vblock(p, l, t, NMV);
;         else if (t < NMV + NAT) attn_block_task(p, l, t - NMV);
;         else gate_tile(t - NMV - NAT, (const bf16_t*)(p->ws + OFF_XB), (const bf16_t*)(p->ws + OFF_WG), (bf16_t*)(p->ws + OFF_G), (bf16_t*)smem);
.LBB0_174:
	s_or_b64 exec, exec, s[14:15]
	s_waitcnt lgkmcnt(0)
	s_barrier
	ds_read_b32 v0, v235 offset:16
	s_mov_b64 s[12:13], -1
	s_waitcnt lgkmcnt(0)
	v_readfirstlane_b32 s74, v0
	v_readlane_b32 s2, v234, 8
	s_cmp_lg_u32 s2, 0
	s_cbranch_scc1 .Lq_xcd
	s_cmpk_gt_i32 s74, 0xff
	s_cbranch_scc0 .LBB0_189
	s_cmpk_gt_u32 s74, 0x57f
	s_cbranch_scc0 .LBB0_180
	v_readlane_b32 s2, v231, 56
	s_and_b32 s2, s2, 7
	s_lshl_b32 s2, s2, 2
	s_add_i32 s2, s2, 4
	v_writelane_b32 v234, s2, 8
	s_branch .LBB0_170
.Lq_xcd:
	s_cmpk_lt_u32 s74, 0x220
	s_cbranch_scc0 .LBB0_169
	s_lshr_b32 s14, s2, 2
	s_add_i32 s14, s14, -1
	s_mul_i32 s15, s74, 0x1e2
	s_lshr_b32 s15, s15, 16
	s_mul_i32 s18, s15, 0x88
	s_sub_i32 s18, s74, s18
	s_lshr_b32 s19, s18, 3
	s_and_b32 s18, s18, 7
	s_mul_i32 s14, s14, 17
	s_add_i32 s14, s14, s19
	s_lshl_b32 s15, s15, 3
	s_add_i32 s15, s15, s18
	s_lshl_b32 s14, s14, 5
	s_add_i32 s74, s14, s15
	s_addk_i32 s74, 0x580
	v_mov_b32_e32 v12, v192
	v_mov_b32_e32 v40, v192
	s_add_i32 s2, s74, 0xfffffa80
	v_ashrrev_i32_e32 v0, 31, v40
	s_waitcnt vmcnt(6)
	v_ashrrev_i32_e32 v30, 3, v40
	v_lshrrev_b32_e32 v0, 26, v0
	v_add_u32_e32 v0, v30, v0
	v_lshrrev_b32_e32 v1, 6, v0
	v_mul_i32_i24_e32 v1, 64, v1
	v_sub_u32_e32 v1, v30, v1
	v_lshrrev_b16_sdwa v2, v196, sext(v1) dst_sel:DWORD dst_unused:UNUSED_PAD src0_sel:DWORD src1_sel:BYTE_0
	v_and_b32_e32 v2, 3, v2
	v_add_u16_e32 v2, v1, v2
	v_ashrrev_i16_sdwa v3, v197, sext(v2) dst_sel:DWORD dst_unused:UNUSED_PAD src0_sel:DWORD src1_sel:BYTE_0
	v_and_b32_e32 v2, 0xfc, v2
	v_sub_u16_e32 v1, v1, v2
	v_and_b32_e32 v0, 0x7ffffc0, v0
	v_lshlrev_b32_sdwa v1, v198, sext(v1) dst_sel:DWORD dst_unused:UNUSED_PAD src0_sel:DWORD src1_sel:BYTE_0
	v_bfe_i32 v2, v3, 0, 16
	v_add3_u32 v41, v0, v2, v1
	v_add_u32_e32 v0, 32, v30
	v_ashrrev_i32_e32 v1, 31, v0
	v_lshrrev_b32_e32 v1, 26, v1
	v_add_u32_e32 v1, v0, v1
	v_lshrrev_b32_e32 v2, 6, v1
	v_mul_i32_i24_e32 v2, 64, v2
	v_sub_u32_e32 v0, v0, v2
	v_lshrrev_b16_sdwa v2, v196, sext(v0) dst_sel:DWORD dst_unused:UNUSED_PAD src0_sel:DWORD src1_sel:BYTE_0
	v_and_b32_e32 v2, 3, v2
	v_add_u16_e32 v2, v0, v2
	v_ashrrev_i16_sdwa v3, v197, sext(v2) dst_sel:DWORD dst_unused:UNUSED_PAD src0_sel:DWORD src1_sel:BYTE_0
	v_and_b32_e32 v2, 0xfc, v2
	v_sub_u16_e32 v0, v0, v2
	v_and_b32_e32 v1, 0x7ffffc0, v1
	v_lshlrev_b32_sdwa v0, v198, sext(v0) dst_sel:DWORD dst_unused:UNUSED_PAD src0_sel:DWORD src1_sel:BYTE_0
	v_bfe_i32 v2, v3, 0, 16
	v_add3_u32 v42, v1, v2, v0
	v_add_u32_e32 v0, 64, v30
	v_ashrrev_i32_e32 v1, 31, v0
	v_lshrrev_b32_e32 v1, 26, v1
	v_add_u32_e32 v1, v0, v1
	v_lshrrev_b32_e32 v2, 6, v1
	v_mul_i32_i24_e32 v2, 64, v2
	v_sub_u32_e32 v0, v0, v2
	v_lshrrev_b16_sdwa v2, v196, sext(v0) dst_sel:DWORD dst_unused:UNUSED_PAD src0_sel:DWORD src1_sel:BYTE_0
	v_and_b32_e32 v2, 3, v2
	v_add_u16_e32 v2, v0, v2
	v_ashrrev_i16_sdwa v3, v197, sext(v2) dst_sel:DWORD dst_unused:UNUSED_PAD src0_sel:DWORD src1_sel:BYTE_0
	v_and_b32_e32 v2, 0xfc, v2
	v_sub_u16_e32 v0, v0, v2
	v_and_b32_e32 v1, 0x7ffffc0, v1
	v_lshlrev_b32_sdwa v0, v198, sext(v0) dst_sel:DWORD dst_unused:UNUSED_PAD src0_sel:DWORD src1_sel:BYTE_0
	v_bfe_i32 v2, v3, 0, 16
	v_add3_u32 v43, v1, v2, v0
	v_add_u32_e32 v0, 0x60, v30
	v_ashrrev_i32_e32 v1, 31, v0
	v_lshrrev_b32_e32 v1, 26, v1
	v_add_u32_e32 v1, v0, v1
	v_lshrrev_b32_e32 v2, 6, v1
	v_mul_i32_i24_e32 v2, 64, v2
	v_sub_u32_e32 v0, v0, v2
	s_lshr_b32 s13, s2, 5
	v_lshrrev_b16_sdwa v2, v196, sext(v0) dst_sel:DWORD dst_unused:UNUSED_PAD src0_sel:DWORD src1_sel:BYTE_0
	s_lshl_b32 s86, s13, 17
	v_and_b32_e32 v2, 3, v2
	s_and_b32 s12, s74, 31
	s_lshl_b64 s[14:15], s[86:87], 1
	v_add_u16_e32 v2, v0, v2
	s_add_u32 s18, s80, s14
	v_ashrrev_i16_sdwa v3, v197, sext(v2) dst_sel:DWORD dst_unused:UNUSED_PAD src0_sel:DWORD src1_sel:BYTE_0
	v_and_b32_e32 v2, 0xfc, v2
	s_addc_u32 s19, s81, s15
	s_lshl_b32 s2, s12, 18
	v_sub_u16_e32 v0, v0, v2
	s_add_u32 s22, s11, s2
	v_and_b32_e32 v1, 0x7ffffc0, v1
	v_lshlrev_b32_sdwa v0, v198, sext(v0) dst_sel:DWORD dst_unused:UNUSED_PAD src0_sel:DWORD src1_sel:BYTE_0
	v_bfe_i32 v2, v3, 0, 16
	v_ashrrev_i32_e32 v31, 31, v30
	s_addc_u32 s23, s39, 0
	v_add3_u32 v44, v1, v2, v0
	v_lshlrev_b64 v[32:33], 11, v[30:31]
	v_lshlrev_b32_e32 v2, 4, v40
	v_lshl_add_u64 v[0:1], s[22:23], 0, v[32:33]
	v_and_b32_e32 v38, 0x70, v2
	v_mov_b32_e32 v39, v13
	v_lshl_add_u64 v[8:9], v[0:1], 0, v[38:39]
	v_add_co_u32_e32 v0, vcc, s7, v8
	v_mul_lo_u32 v46, v30, s89
	s_nop 0
	v_addc_co_u32_e32 v1, vcc, 0, v9, vcc
	v_add_co_u32_e32 v10, vcc, s37, v8
	v_mov_b32_e32 v250, v8
	v_mov_b32_e32 v251, v9
	s_nop 0
	v_addc_co_u32_e32 v11, vcc, 0, v9, vcc
	v_add_co_u32_e32 v14, vcc, s73, v8
	v_and_b32_e32 v30, 7, v40
	s_nop 0
	v_addc_co_u32_e32 v15, vcc, 0, v9, vcc
	s_nop 0
	v_lshl_add_u64 v[14:15], s[18:19], 0, v[32:33]
	v_lshl_add_u64 v[26:27], v[14:15], 0, v[38:39]
	v_add_co_u32_e32 v14, vcc, s7, v26
	s_add_u32 s14, s58, s14
	s_nop 0
	v_addc_co_u32_e32 v15, vcc, 0, v27, vcc
	v_add_co_u32_e32 v28, vcc, s37, v26
	v_mov_b32_e32 v248, v26
	v_mov_b32_e32 v249, v27
	s_nop 0
	v_addc_co_u32_e32 v29, vcc, 0, v27, vcc
	v_add_co_u32_e32 v34, vcc, s73, v26
	v_and_b32_e32 v31, 15, v40
	s_nop 0
	v_addc_co_u32_e32 v35, vcc, 0, v27, vcc
	s_nop 0
	v_lshrrev_b32_e32 v39, 1, v40
	v_lshl_or_b32 v32, v30, 4, v32
	s_addc_u32 s15, s59, s15
	v_and_or_b32 v31, v39, s3, v31
	v_and_b32_e32 v39, 0x4f, v40
	v_lshl_add_u64 v[98:99], s[14:15], 0, v[32:33]
	s_add_u32 s14, s58, s2
; template <int NT>
; __device__ __forceinline__ void gemm_tile(f32x4 (&acc)[4][NT], const bf16_t* A, int lda, const bf16_t* B, int ldb, int K, bf16_t* sm) {
;     ...
;     const bf16_t* ga = A + (size_t)lrow * lda + lkc * 8;
;     const bf16_t* gb = B + (size_t)lrow * ldb + lkc * 8;
;     int sbrow[NT];
; #pragma unroll
;     for (int i = 0; i < NT; ++i) { const int g = lrow + 32 * i, W_ = 16 * NT, rem = g % W_; sbrow[i] = (g / W_) * W_ + (rem % NT) * 16 + rem / NT; }
;     u32x4 ra0[4], rb0[NT];
; #pragma unroll
;     for (int i = 0; i < 4; ++i) ra0[i] = *(const u32x4*)(ga + (size_t)(32 * i) * lda);
; #pragma unroll
;     for (int i = 0; i < NT; ++i) rb0[i] = *(const u32x4*)(gb + (size_t)(32 * i) * ldb);
;     const int nk = K >> 6;
;     for (int kt = 0; kt < nk; ++kt) {
;         lds_barrier();
; #pragma unroll
;         for (int i = 0; i < 4; ++i) *(u32x4*)(sA + (lrow + 32 * i) * LDT + lkc * 8) = ra0[i];
; #pragma unroll
;         for (int i = 0; i < NT; ++i) *(u32x4*)(sB + sbrow[i] * LDT + lkc * 8) = rb0[i];
;         lds_barrier();
;         if (kt + 1 < nk) {
;             ga += 64; gb += 64;
; #pragma unroll
;             for (int i = 0; i < 4; ++i) ra0[i] = *(const u32x4*)(ga + (size_t)(32 * i) * lda);
; #pragma unroll
;             for (int i = 0; i < NT; ++i) rb0[i] = *(const u32x4*)(gb + (size_t)(32 * i) * ldb);
;         }
	v_and_b32_e32 v45, 48, v40
	v_mul_lo_u32 v31, v31, s89
	v_mul_u32_u24_e32 v39, 0xa0, v39
	v_mul_lo_u32 v41, v41, s89
	v_mul_lo_u32 v42, v42, s89
	v_mul_lo_u32 v43, v43, s89
	v_mul_lo_u32 v44, v44, s89
	s_addc_u32 s15, s59, 0
	v_mov_b32_e32 v30, 0
	v_lshl_add_u64 v[100:101], s[14:15], 0, v[32:33]
	s_mov_b64 s[14:15], 0
	v_add_u32_e32 v104, v38, v46
	v_add_u32_e32 v105, v38, v41
	v_add_u32_e32 v106, v38, v42
	v_add_u32_e32 v107, v38, v43
	v_add_u32_e32 v108, v38, v44
	v_add_u32_e32 v103, v45, v31
	v_add_u32_e32 v102, v45, v39
	v_mov_b32_e32 v31, v30
	v_mov_b32_e32 v32, v30
	v_mov_b32_e32 v33, v30
	v_mov_b32_e32 v38, v30
	v_mov_b32_e32 v39, v30
	v_mov_b32_e32 v40, v30
	v_mov_b32_e32 v41, v30
	v_mov_b32_e32 v42, v30
	v_mov_b32_e32 v43, v30
	v_mov_b32_e32 v44, v30
	v_mov_b32_e32 v45, v30
	v_mov_b32_e32 v46, v30
	v_mov_b32_e32 v47, v30
	v_mov_b32_e32 v48, v30
	v_mov_b32_e32 v49, v30
	v_mov_b32_e32 v50, v30
	v_mov_b32_e32 v51, v30
	v_mov_b32_e32 v52, v30
	v_mov_b32_e32 v53, v30
	v_mov_b32_e32 v54, v30
	v_mov_b32_e32 v55, v30
	v_mov_b32_e32 v56, v30
	v_mov_b32_e32 v57, v30
	v_mov_b32_e32 v58, v30
	v_mov_b32_e32 v59, v30
	v_mov_b32_e32 v60, v30
	v_mov_b32_e32 v61, v30
	v_mov_b32_e32 v62, v30
	v_mov_b32_e32 v63, v30
	v_mov_b32_e32 v64, v30
	v_mov_b32_e32 v65, v30
	v_mov_b32_e32 v66, v30
	v_mov_b32_e32 v67, v30
	v_mov_b32_e32 v68, v30
	v_mov_b32_e32 v69, v30
	v_mov_b32_e32 v70, v30
	v_mov_b32_e32 v71, v30
	v_mov_b32_e32 v72, v30
	v_mov_b32_e32 v73, v30
	v_mov_b32_e32 v74, v30
	v_mov_b32_e32 v75, v30
	v_mov_b32_e32 v76, v30
	v_mov_b32_e32 v77, v30
	v_mov_b32_e32 v78, v30
	v_mov_b32_e32 v79, v30
	v_mov_b32_e32 v80, v30
	v_mov_b32_e32 v81, v30
	v_mov_b32_e32 v82, v30
	v_mov_b32_e32 v83, v30
	v_mov_b32_e32 v84, v30
	v_mov_b32_e32 v85, v30
	v_mov_b32_e32 v86, v30
	v_mov_b32_e32 v87, v30
	v_mov_b32_e32 v88, v30
	v_mov_b32_e32 v89, v30
	v_mov_b32_e32 v90, v30
	v_mov_b32_e32 v91, v30
	v_mov_b32_e32 v92, v30
	v_mov_b32_e32 v93, v30
	v_mov_b32_e32 v94, v30
	v_mov_b32_e32 v95, v30
	v_mov_b32_e32 v96, v30
	v_mov_b32_e32 v97, v30
	v_writelane_b32 v234, s90, 0
	v_writelane_b32 v234, s91, 1
	v_writelane_b32 v234, s92, 2
	v_writelane_b32 v234, s93, 3
	v_writelane_b32 v234, s94, 4
	v_writelane_b32 v234, s95, 5
	v_bfe_u32 v160, v192, 3, 3
	v_and_b32_e32 v161, 7, v192
	v_xor_b32_e32 v161, v160, v161
	v_lshlrev_b32_e32 v161, 4, v161
	v_lshrrev_b32_e32 v162, 6, v192
	v_lshl_add_u32 v163, v162, 5, v160
	v_mul_u32_u24_e32 v163, 0x800, v163
	v_add_u32_e32 v236, v163, v161
	v_add_u32_e32 v237, 0x3c00, v236
	v_add_u32_e32 v238, 0x3c00, v237
	v_add_u32_e32 v239, 0x3c00, v238
	v_lshrrev_b32_e32 v163, 7, v192
	v_bfe_u32 v162, v192, 6, 1
	v_lshlrev_b32_e32 v163, 6, v163
	v_lshl_add_u32 v163, v160, 2, v163
	v_lshl_add_u32 v163, v162, 1, v163
	v_mul_u32_u24_e32 v163, 0x800, v163
	v_add_u32_e32 v240, v163, v161
	v_add_u32_e32 v241, 0xfc00, v240
	v_subrev_u32_e32 v242, 0xfc00, v241
	v_add_u32_e32 v243, 0xfc00, v242
	v_and_b32_e32 v160, 15, v192
	v_bfe_u32 v161, v192, 4, 2
	v_and_b32_e32 v162, 7, v160
	v_xor_b32_e32 v161, v161, v162
	v_lshlrev_b32_e32 v161, 4, v161
	v_lshl_add_u32 v161, v160, 7, v161
	v_lshrrev_b32_e32 v162, 7, v192
	v_lshl_add_u32 v244, v162, 13, v161
	v_bfe_u32 v162, v192, 6, 1
	v_lshl_add_u32 v246, v162, 13, v161
	v_add_u32_e32 v246, 0x4000, v246
	v_xor_b32_e32 v245, 64, v244
	v_xor_b32_e32 v247, 64, v246
	v_lshrrev_b32_e32 v160, 6, v192
	s_nop 0
	v_readfirstlane_b32 s94, v160
	v_readfirstlane_b32 s90, v248
	v_readfirstlane_b32 s91, v249
	v_readfirstlane_b32 s92, v250
	v_readfirstlane_b32 s93, v251
	s_mul_i32 s95, s94, 0x4000
	s_sub_u32 s90, s90, s95
	s_subb_u32 s91, s91, 0
	s_mul_i32 s95, s94, 0x4000
	s_sub_u32 s92, s92, s95
	s_subb_u32 s93, s93, 0
	s_lshl_b32 s94, s94, 10
	s_waitcnt lgkmcnt(0)
	s_barrier
	s_lshl_b32 s95, s94, 2
	s_add_u32 m0, s95, 0x0
	s_nop 0
	global_load_lds_dwordx4 v236, s[90:91]
	global_load_lds_dwordx4 v237, s[90:91] offset:1024
	global_load_lds_dwordx4 v238, s[90:91] offset:2048
	global_load_lds_dwordx4 v239, s[90:91] offset:3072
	s_mul_i32 s95, s94, 4
	s_add_u32 m0, s95, 0x4000
	s_nop 0
	global_load_lds_dwordx4 v240, s[92:93]
	global_load_lds_dwordx4 v241, s[92:93] offset:1024
	global_load_lds_dwordx4 v242, s[92:93] offset:2048
	global_load_lds_dwordx4 v243, s[92:93] offset:3072
	s_add_u32 s90, s90, 0x80
	s_addc_u32 s91, s91, 0
	s_add_u32 s92, s92, 0x80
	s_addc_u32 s93, s93, 0
	s_waitcnt vmcnt(0)
	s_barrier
	s_lshl_b32 s95, s94, 2
	s_add_u32 m0, s95, 0x8000
	s_nop 0
	global_load_lds_dwordx4 v236, s[90:91]
	global_load_lds_dwordx4 v237, s[90:91] offset:1024
	global_load_lds_dwordx4 v238, s[90:91] offset:2048
	global_load_lds_dwordx4 v239, s[90:91] offset:3072
	s_mul_i32 s95, s94, 4
	s_add_u32 m0, s95, 0xc000
	s_nop 0
	global_load_lds_dwordx4 v240, s[92:93]
	global_load_lds_dwordx4 v241, s[92:93] offset:1024
	global_load_lds_dwordx4 v242, s[92:93] offset:2048
	global_load_lds_dwordx4 v243, s[92:93] offset:3072
	s_add_u32 s90, s90, 0x80
	s_addc_u32 s91, s91, 0
	s_add_u32 s92, s92, 0x80
	s_addc_u32 s93, s93, 0
	ds_read_b128 v[110:113], v244 offset:0
	ds_read_b128 v[114:117], v244 offset:2048
	ds_read_b128 v[118:121], v244 offset:4096
	ds_read_b128 v[122:125], v244 offset:6144
	ds_read_b128 v[126:129], v246 offset:0
	ds_read_b128 v[130:133], v246 offset:2048
	ds_read_b128 v[134:137], v246 offset:4096
	ds_read_b128 v[138:141], v246 offset:6144
	s_movk_i32 s95, 0x6
	s_cmp_eq_u32 s95, 0
	s_cbranch_scc1 .Lgemm_x178
